# in-proj epilogue rewritten (region select once per unit) + mixer queue order: GEMM units before attention items
# baseline (speedup 1.0000x reference)
; #define WIDE_STORE(BASE, LD, COFF, O) do { if ((m & 1) == 0) opend[n] = (O); \
;                 else *(uint4*)((BASE) + (size_t)tok * (LD) + (ncw - (COFF))) = swap_pair(opend[n], (O)); } while (0)
; __device__ __forceinline__ uint4 swap_pair(const uint2 a, const uint2 b) {
;   const auto rx = __builtin_amdgcn_permlane16_swap(a.x, b.x, false, false);
;   const auto ry = __builtin_amdgcn_permlane16_swap(a.y, b.y, false, false);
;   return make_uint4(rx[0], ry[0], rx[1], ry[1]);
; }
;     ...
;             for (int n = 0; n < 2; ++n) {
;               const int nc = brow + ai * 128 + wr * 64 + m * 16 + fq * 4;
;               const int tok = bcol + bj * 128 + wc * 32 + n * 16 + fr;
;               const int ncw = brow + ai * 128 + wr * 64 + ((m & ~1) + (fq & 1)) * 16 + (fq & ~1) * 4;
;     ...
;               f32x4 v = acc[ai][bj][m][n];
;               if (MODE == 0) {
;                 if (tn == 52) {
;                   if (ai == 0) *(float4*)((float*)(ws + OFF_DTR) + (size_t)tok * 128 + (nc - 13312)) = make_float4(v[0], v[1], v[2], v[3]);
;                 } else {
;                   u16* dst; int ld, c0;
;                   if (tn < 16) { dst = (u16*)(ws + OFF_Z); ld = 4096; c0 = 0; }
;                   else if (tn < 40) { dst = (u16*)(ws + OFF_RA); ld = 6144; c0 = 4096; }
;                   else if (tn < 48) { dst = (u16*)(ws + OFF_Q); ld = 2048; c0 = 10240; }
;                   else if (tn < 50) { dst = (u16*)(ws + OFF_K); ld = 512; c0 = 12288; }
;                   else { dst = (u16*)(ws + OFF_V); ld = 512; c0 = 12800; }
;                   uint2 o; o.x = pk2(v[0], v[1]); o.y = pk2(v[2], v[3]);
;                   WIDE_STORE(dst, ld, c0, o);
;                 }
.LBB0_184:
	v_and_b32_e32 v152, 15, v140
	v_or_b32_e32 v152, s54, v152
	v_or_b32_e32 v152, s10, v152
	v_lshrrev_b32_e32 v153, 2, v140
	v_and_b32_e32 v154, -4, v153
	s_add_i32 s1, s0, s49
	s_cmp_eq_u32 s30, 52
	s_cbranch_scc1 .Lm0_dt
	s_mov_b32 s2, 0x26700000
	s_movk_i32 s6, 0x2000
	s_mov_b32 s7, 0
	s_cmp_lt_u32 s30, 16
	s_cbranch_scc1 .Lm0_sel
	s_mov_b32 s2, 0xa700000
	s_movk_i32 s6, 0x3000
	s_movk_i32 s7, 0x2000
	s_cmp_lt_u32 s30, 40
	s_cbranch_scc1 .Lm0_sel
	s_mov_b32 s2, 0x2e700000
	s_movk_i32 s6, 0x1000
	s_movk_i32 s7, 0x5000
	s_cmp_lt_u32 s30, 48
	s_cbranch_scc1 .Lm0_sel
	s_mov_b32 s2, 0x32700000
	s_movk_i32 s6, 0x400
	s_movk_i32 s7, 0x6000
	s_cmp_lt_u32 s30, 50
	s_cbranch_scc1 .Lm0_sel
	s_mov_b32 s2, 0x33700000
	s_movk_i32 s7, 0x6400
.Lm0_sel:
	s_add_u32 s2, s50, s2
	s_addc_u32 s3, s51, 0
	s_lshl_b32 s1, s1, 1
	s_sub_i32 s1, s1, s7
	v_and_b32_e32 v153, -8, v153
	v_and_b32_e32 v155, 16, v140
	v_add_u32_e32 v153, v153, v155
	v_mul_lo_u32 v134, v152, s6
	v_lshl_add_u32 v134, v153, 1, v134
	v_add_u32_e32 v134, s1, v134
	s_lshl_b32 s20, s6, 4
	s_lshl_b32 s32, s6, 7
	v_add_u32_e32 v135, s20, v134
	v_add_u32_e32 v136, s32, v134
	v_add_u32_e32 v137, s20, v136
	v_cvt_pk_bf16_f32 v126, v126, v127
	v_cvt_pk_bf16_f32 v127, v128, v129
	v_cvt_pk_bf16_f32 v128, v118, v119
	v_cvt_pk_bf16_f32 v129, v120, v121
	v_cvt_pk_bf16_f32 v110, v110, v111
	v_cvt_pk_bf16_f32 v111, v112, v113
	v_cvt_pk_bf16_f32 v112, v102, v103
	v_cvt_pk_bf16_f32 v113, v104, v105
	s_nop 1
	v_permlane16_swap_b32_e32 v126, v128
	v_permlane16_swap_b32_e32 v127, v129
	v_permlane16_swap_b32_e32 v110, v112
	v_permlane16_swap_b32_e32 v111, v113
	global_store_dwordx4 v134, v[126:129], s[2:3] offset:0
	global_store_dwordx4 v134, v[110:113], s[2:3] offset:64
	v_cvt_pk_bf16_f32 v122, v122, v123
	v_cvt_pk_bf16_f32 v123, v124, v125
	v_cvt_pk_bf16_f32 v124, v114, v115
	v_cvt_pk_bf16_f32 v125, v116, v117
	v_cvt_pk_bf16_f32 v106, v106, v107
	v_cvt_pk_bf16_f32 v107, v108, v109
	v_cvt_pk_bf16_f32 v108, v98, v99
	v_cvt_pk_bf16_f32 v109, v100, v101
	s_nop 1
	v_permlane16_swap_b32_e32 v122, v124
	v_permlane16_swap_b32_e32 v123, v125
	v_permlane16_swap_b32_e32 v106, v108
	v_permlane16_swap_b32_e32 v107, v109
	global_store_dwordx4 v135, v[122:125], s[2:3] offset:0
	global_store_dwordx4 v135, v[106:109], s[2:3] offset:64
	v_cvt_pk_bf16_f32 v94, v94, v95
	v_cvt_pk_bf16_f32 v95, v96, v97
	v_cvt_pk_bf16_f32 v96, v86, v87
	v_cvt_pk_bf16_f32 v97, v88, v89
	v_cvt_pk_bf16_f32 v78, v78, v79
	v_cvt_pk_bf16_f32 v79, v80, v81
	v_cvt_pk_bf16_f32 v80, v70, v71
	v_cvt_pk_bf16_f32 v81, v72, v73
	s_nop 1
	v_permlane16_swap_b32_e32 v94, v96
	v_permlane16_swap_b32_e32 v95, v97
	v_permlane16_swap_b32_e32 v78, v80
	v_permlane16_swap_b32_e32 v79, v81
	global_store_dwordx4 v136, v[94:97], s[2:3] offset:0
	global_store_dwordx4 v136, v[78:81], s[2:3] offset:64
	v_cvt_pk_bf16_f32 v90, v90, v91
	v_cvt_pk_bf16_f32 v91, v92, v93
	v_cvt_pk_bf16_f32 v92, v82, v83
	v_cvt_pk_bf16_f32 v93, v84, v85
	v_cvt_pk_bf16_f32 v74, v74, v75
	v_cvt_pk_bf16_f32 v75, v76, v77
	v_cvt_pk_bf16_f32 v76, v64, v65
	v_cvt_pk_bf16_f32 v77, v66, v67
	s_nop 1
	v_permlane16_swap_b32_e32 v90, v92
	v_permlane16_swap_b32_e32 v91, v93
	v_permlane16_swap_b32_e32 v74, v76
	v_permlane16_swap_b32_e32 v75, v77
	global_store_dwordx4 v137, v[90:93], s[2:3] offset:0
	global_store_dwordx4 v137, v[74:77], s[2:3] offset:64
	v_cvt_pk_bf16_f32 v60, v60, v61
	v_cvt_pk_bf16_f32 v61, v62, v63
	v_cvt_pk_bf16_f32 v62, v52, v53
	v_cvt_pk_bf16_f32 v63, v54, v55
	v_cvt_pk_bf16_f32 v44, v44, v45
	v_cvt_pk_bf16_f32 v45, v46, v47
	v_cvt_pk_bf16_f32 v46, v36, v37
	v_cvt_pk_bf16_f32 v47, v38, v39
	s_nop 1
	v_permlane16_swap_b32_e32 v60, v62
	v_permlane16_swap_b32_e32 v61, v63
	v_permlane16_swap_b32_e32 v44, v46
	v_permlane16_swap_b32_e32 v45, v47
	global_store_dwordx4 v134, v[60:63], s[2:3] offset:256
	global_store_dwordx4 v134, v[44:47], s[2:3] offset:320
	v_cvt_pk_bf16_f32 v56, v56, v57
	v_cvt_pk_bf16_f32 v57, v58, v59
	v_cvt_pk_bf16_f32 v58, v48, v49
	v_cvt_pk_bf16_f32 v59, v50, v51
	v_cvt_pk_bf16_f32 v40, v40, v41
	v_cvt_pk_bf16_f32 v41, v42, v43
	v_cvt_pk_bf16_f32 v42, v32, v33
	v_cvt_pk_bf16_f32 v43, v34, v35
	s_nop 1
	v_permlane16_swap_b32_e32 v56, v58
	v_permlane16_swap_b32_e32 v57, v59
	v_permlane16_swap_b32_e32 v40, v42
	v_permlane16_swap_b32_e32 v41, v43
	global_store_dwordx4 v135, v[56:59], s[2:3] offset:256
	global_store_dwordx4 v135, v[40:43], s[2:3] offset:320
	v_cvt_pk_bf16_f32 v28, v28, v29
	v_cvt_pk_bf16_f32 v29, v30, v31
	v_cvt_pk_bf16_f32 v30, v20, v21
	v_cvt_pk_bf16_f32 v31, v22, v23
	v_cvt_pk_bf16_f32 v12, v12, v13
	v_cvt_pk_bf16_f32 v13, v14, v15
	v_cvt_pk_bf16_f32 v14, v4, v5
	v_cvt_pk_bf16_f32 v15, v6, v7
	s_nop 1
	v_permlane16_swap_b32_e32 v28, v30
	v_permlane16_swap_b32_e32 v29, v31
	v_permlane16_swap_b32_e32 v12, v14
	v_permlane16_swap_b32_e32 v13, v15
	global_store_dwordx4 v136, v[28:31], s[2:3] offset:256
	global_store_dwordx4 v136, v[12:15], s[2:3] offset:320
	v_cvt_pk_bf16_f32 v24, v24, v25
	v_cvt_pk_bf16_f32 v25, v26, v27
	v_cvt_pk_bf16_f32 v26, v16, v17
	v_cvt_pk_bf16_f32 v27, v18, v19
	v_cvt_pk_bf16_f32 v8, v8, v9
	v_cvt_pk_bf16_f32 v9, v10, v11
	v_cvt_pk_bf16_f32 v10, v0, v1
	v_cvt_pk_bf16_f32 v11, v2, v3
	s_nop 1
	v_permlane16_swap_b32_e32 v24, v26
	v_permlane16_swap_b32_e32 v25, v27
	v_permlane16_swap_b32_e32 v8, v10
	v_permlane16_swap_b32_e32 v9, v11
	global_store_dwordx4 v137, v[24:27], s[2:3] offset:256
	global_store_dwordx4 v137, v[8:11], s[2:3] offset:320
	s_branch .Lm0_done
.Lm0_dt:
	s_add_u32 s2, s50, 0x34700000
	s_addc_u32 s3, s51, 0
	v_add_u32_e32 v154, s49, v154
	v_lshlrev_b32_e32 v134, 9, v152
	v_lshl_add_u32 v134, v154, 2, v134
	v_add_u32_e32 v135, 0x2000, v134
	v_add_u32_e32 v136, 0x10000, v134
	v_add_u32_e32 v137, 0x12000, v134
	global_store_dwordx4 v134, v[126:129], s[2:3] offset:0
	global_store_dwordx4 v134, v[118:121], s[2:3] offset:64
	global_store_dwordx4 v134, v[110:113], s[2:3] offset:128
	global_store_dwordx4 v134, v[102:105], s[2:3] offset:192
	global_store_dwordx4 v135, v[122:125], s[2:3] offset:0
	global_store_dwordx4 v135, v[114:117], s[2:3] offset:64
	global_store_dwordx4 v135, v[106:109], s[2:3] offset:128
	global_store_dwordx4 v135, v[98:101], s[2:3] offset:192
	global_store_dwordx4 v136, v[94:97], s[2:3] offset:0
	global_store_dwordx4 v136, v[86:89], s[2:3] offset:64
	global_store_dwordx4 v136, v[78:81], s[2:3] offset:128
	global_store_dwordx4 v136, v[70:73], s[2:3] offset:192
	global_store_dwordx4 v137, v[90:93], s[2:3] offset:0
	global_store_dwordx4 v137, v[82:85], s[2:3] offset:64
	global_store_dwordx4 v137, v[74:77], s[2:3] offset:128
	global_store_dwordx4 v137, v[64:67], s[2:3] offset:192
.Lm0_done:
	v_readlane_b32 s34, v243, 2
	v_readlane_b32 s31, v244, 61
	v_readlane_b32 s35, v243, 3
	v_readlane_b32 s18, v243, 4
.LBB0_268:
	s_waitcnt vmcnt(0)
	s_and_b64 s[0:1], s[56:57], s[8:9]
	s_andn2_b64 vcc, exec, s[0:1]
	s_cbranch_vccnz .LBB0_177
	s_barrier
	s_branch .LBB0_177

; #define STAGE(P_, BASE, br, kt) do { const u16* _gb = (BASE) + (long)(br) * K + (long)(kt) * BK; \
;     _Pragma("unroll") for (int _i = 0; _i < 2; ++_i) { \
;       __builtin_amdgcn_global_load_lds((const unsigned*)(_gb + (long)_i * 64 * K + lane_off), \
;         (unsigned*)((char*)(P_) + lds_wbase + _i * 8192), 16, 0, 0); } } while (0)
; #define WAIT_V(n) asm volatile("s_waitcnt vmcnt(" #n ")" ::: "memory")
; #define BAR __builtin_amdgcn_s_barrier()
; template <int PRE> ...
;     ...
;   if (PRE == 2) {
;     STAGE(SB(0, 0), Bt, bcol, 0); STAGE(SA(0, 0), A, brow, 0);
;     STAGE(SB(0, 1), Bt, bcol + HALF, 0); STAGE(SA(0, 1), A, brow + HALF, 0);
;     if (wr == 1) BAR;
;     WAIT_V(4); BAR;
;     STAGE(SB(1, 0), Bt, bcol, 1); STAGE(SA(1, 0), A, brow, 1); STAGE(SB(1, 1), Bt, bcol + HALF, 1);
;     WAIT_V(6); BAR;
; __device__ __forceinline__ void mixer_phase(const Params& P, const int pass, const int wvi) {
;     ...
;   for (int qq = 0; qq < 8; ++qq) {
;     const int q = (myq + qq) & 7;
;     while (true) {
;       if (tidm == 0) s_item = atomicAdd(ctr + q, 1);
;       __syncthreads();
;       const int itx = s_item;
;       __syncthreads();
;       if (itx >= total_q) break;
;       if (itx < n_ssd_q) {
;         int b, combo;
;         if (pass == 0) { b = q; combo = itx >> 3; } else { b = 0; combo = 2 * q + (itx >> 3); }
;         const int g = combo >> 1, dir = combo & 1, h = g * 8 + (itx & 7);
;         ssd_item(P, pass, (b << 7) | (h << 1) | dir, wvi);
;       } else if (itx < n_mix_q) {
;         const int a = itx - n_ssd_q;
;         attn_item(P, pass, ((q * 16 + (a >> 4)) << 4) | (a & 15), wvi);
;       } else if (itx < n_gate_q) {
;         const int gu = itx - n_mix_q;
;         const int u = (q * 2 + (gu >> 6)) * 64 + (gu & 63);
;         gemm_phase<1>(P, pass, wvi, u, 1 << 20, u + 1);
;         __syncthreads();
;       } else {
;         const int u = 15 * 64 + q * 8 + (itx - n_gate_q);
;         gemm_phase<0>(P, pass, wvi, u, 1 << 20, u + 1);
.LBB0_445:
	s_or_b64 exec, exec, s[0:1]
	s_waitcnt lgkmcnt(0)
	s_barrier
	ds_read_b32 v0, v145 offset:20
	s_mov_b64 s[0:1], -1
	s_waitcnt lgkmcnt(0)
	s_barrier
	v_cmp_le_i32_e32 vcc, s25, v0
	v_readfirstlane_b32 s12, v0
	s_cbranch_vccnz .LBB0_440
	s_sub_i32 s14, s12, s24
	s_cmp_lt_i32 s14, 0
	s_cbranch_scc1 .Lmix_keep
	s_add_i32 s16, s12, 0x100
	s_addk_i32 s12, 0xff78
	s_cmp_lt_u32 s14, 0x88
	s_cselect_b32 s12, s16, s12
.Lmix_keep:
	s_cmp_ge_i32 s12, s24
	s_cbranch_scc0 .LBB0_628
	v_readlane_b32 s0, v243, 53
	s_cmp_ge_i32 s12, s0
	s_mov_b64 s[0:1], -1
	s_cbranch_scc0 .LBB0_554
	v_readlane_b32 s0, v243, 54
	s_cmp_ge_i32 s12, s0
	s_mov_b64 s[0:1], -1
	s_cbranch_scc0 .LBB0_546
	s_waitcnt vmcnt(10)
	v_mbcnt_lo_u32_b32 v8, -1, 0
	v_mbcnt_hi_u32_b32 v8, -1, v8
	v_readlane_b32 s0, v243, 54
	v_add_u32_e32 v0, s48, v8
	v_ashrrev_i32_e32 v2, 31, v0
	v_lshrrev_b32_e32 v2, 26, v2
	v_lshlrev_b32_e32 v1, 4, v0
	v_add_u32_e32 v2, v0, v2
	v_bfe_i32 v0, v0, 27, 1
	v_lshrrev_b32_e32 v0, 22, v0
	v_add_u32_e32 v0, v1, v0
	v_and_b32_e32 v0, 0xfffffc00, v0
	v_sub_u32_e32 v0, v1, v0
	v_lshrrev_b32_e32 v1, 4, v0
	v_bitop3_b32 v0, v1, v0, 32 bitop3:0x6c
	s_sub_i32 s13, s12, s0
	v_readlane_b32 s0, v242, 3
	v_ashrrev_i32_e32 v4, 6, v2
	v_ashrrev_i32_e32 v2, 31, v0
	s_add_i32 s13, s13, s0
	v_lshrrev_b32_e32 v2, 26, v2
	s_lshl_b32 s0, s13, 2
	v_lshlrev_b32_e32 v1, 3, v4
	v_add_u32_e32 v2, v0, v2
	s_and_b32 s18, s0, 0x7fffff00
	s_lshl_b32 s0, s13, 20
	v_and_b32_e32 v1, 0x1ffff0, v1
	v_ashrrev_i32_e32 v5, 6, v2
	v_lshlrev_b32_e32 v3, 5, v4
	v_and_b32_e32 v2, 0xc0, v2
	s_and_b32 s0, s0, 0x3f00000
	v_add_u32_e32 v1, v5, v1
	v_and_b32_e32 v6, 32, v3
	v_sub_u32_e32 v0, v0, v2
	v_ashrrev_i16_sdwa v7, v197, sext(v0) dst_sel:DWORD dst_unused:UNUSED_PAD src0_sel:DWORD src1_sel:BYTE_0
	v_lshl_or_b32 v0, v1, 11, v6
	s_add_u32 s0, s33, s0
	v_readlane_b32 s2, v246, 48
	v_add_u32_sdwa v144, v0, sext(v7) dst_sel:DWORD dst_unused:UNUSED_PAD src0_sel:DWORD src1_sel:WORD_0
	s_addc_u32 s1, s92, 0
	s_add_i32 s14, s2, 32
	v_lshlrev_b64 v[130:131], 1, v[144:145]
	s_add_i32 s15, s14, 0x10000
	s_add_i32 s16, s14, 0x12000
	s_lshl_b64 s[2:3], s[18:19], 12
	v_lshl_add_u64 v[0:1], s[0:1], 0, v[130:131]
	s_mov_b32 m0, s15
	s_add_u32 s2, s94, s2
	global_load_lds_dwordx4 v[0:1], off
	v_lshl_add_u64 v[2:3], v[0:1], 0, s[86:87]
	s_mov_b32 m0, s16
	s_addc_u32 s3, s95, s3
	global_load_lds_dwordx4 v[2:3], off
	v_lshl_add_u64 v[2:3], s[2:3], 0, v[130:131]
	s_mov_b32 m0, s14
	s_add_i32 s17, s14, 0x2000
	global_load_lds_dwordx4 v[2:3], off
	v_lshl_add_u64 v[10:11], v[2:3], 0, s[86:87]
	s_mov_b32 m0, s17
	s_mov_b64 s[2:3], 0x80000
	s_add_i32 s20, s14, 0x14000
	global_load_lds_dwordx4 v[10:11], off
	v_lshl_add_u64 v[10:11], v[0:1], 0, s[2:3]
	s_mov_b32 m0, s20
	s_mov_b64 s[2:3], 0xc0000
	s_bitset1_b32 s18, 7
	global_load_lds_dwordx4 v[10:11], off
	v_lshl_add_u64 v[10:11], v[0:1], 0, s[2:3]
	s_add_i32 s21, s14, 0x16000
	s_lshl_b64 s[2:3], s[18:19], 12
	s_add_u32 s2, s94, s2
	s_mov_b32 m0, s21
	s_addc_u32 s3, s95, s3
	s_add_i32 s22, s14, 0x4000
	global_load_lds_dwordx4 v[10:11], off
	v_lshl_add_u64 v[10:11], s[2:3], 0, v[130:131]
	s_mov_b32 m0, s22
	s_add_i32 s23, s14, 0x6000
	global_load_lds_dwordx4 v[10:11], off
	v_lshl_add_u64 v[10:11], v[10:11], 0, s[86:87]
	s_mov_b32 m0, s23
	v_readlane_b32 s2, v243, 49
	global_load_lds_dwordx4 v[10:11], off
	v_readlane_b32 s3, v243, 50
	s_and_b64 vcc, exec, s[2:3]
	s_cbranch_vccnz .LBB0_451
	s_barrier
